# ssm scan: preload all 64 chunk-state values once and reuse in both passes; attention bias table staged with batched loads
# baseline (speedup 1.0000x reference)
; __device__ __forceinline__ unsigned short f2bf(float f) { return (unsigned short)(cvt_pk_bf16(f, 0.f) & 0xffffu); }
; __device__ void ssm_scan_item(const Params& p, int b, int g, LAS unsigned char* lds) {
;     ...
;   { float sr = carry[w * 128 + lane], si = carry[w * 128 + 64 + lane];
; #pragma unroll 32
;     for (int n = w * 32; n < w * 32 + 32; ++n) { const float ar = SL[(size_t)n * 128 + lane], ai = SL[(size_t)n * 128 + 64 + lane];
;       UGs[(size_t)n * 384 + lane] = f2bf(sr); UGs[(size_t)n * 384 + 64 + lane] = f2bf(si);
;       const float nr = l16r * sr - l16i * si + ar, ni = l16r * si + l16i * sr + ai; sr = nr; si = ni; } }
.LBB0_741:
	s_mul_i32 s0, s75, 0x300
	s_mul_hi_u32 s1, s74, 0x300
	s_add_i32 s1, s1, s0
	s_mul_i32 s0, s74, 0x300
	s_add_u32 s0, s88, s0
	s_addc_u32 s1, s89, s1
	v_lshlrev_b32_e32 v52, 1, v144
	s_waitcnt lgkmcnt(0)
	s_barrier
	ds_read2st64_b32 v[114:115], v36 offset0:16 offset1:17
	v_lshl_add_u64 v[36:37], s[0:1], 0, v[52:53]
	v_mov_b32_e32 v52, v184
	v_mov_b32_e32 v116, v185
	s_mov_b64 s[0:1], 0x37c14e00
	v_lshl_add_u64 v[36:37], v[36:37], 0, s[0:1]
	s_waitcnt lgkmcnt(0)
	v_cvt_pk_bf16_f32 v117, v114, v53
	v_mad_u64_u32 v[90:91], s[0:1], s56, v112, v[36:37]
	global_store_short v[90:91], v117, off
	v_cvt_pk_bf16_f32 v117, v115, v53
	global_store_short v[90:91], v117, off offset:128
	v_mul_f32_e32 v90, v89, v115
	v_fma_f32 v90, v113, v114, -v90
	v_add_f32_e32 v52, v52, v90
	v_mul_f32_e32 v90, v113, v115
	v_fmac_f32_e32 v90, v89, v114
	v_mov_b32_e32 v91, v186
	v_mov_b32_e32 v114, v187
	v_add_f32_e32 v90, v90, v116
	v_cvt_pk_bf16_f32 v115, v52, v53
	v_mad_u64_u32 v[50:51], s[0:1], s46, v112, v[36:37]
	global_store_short v[50:51], v115, off
	v_cvt_pk_bf16_f32 v115, v90, v53
	global_store_short v[50:51], v115, off offset:128
	v_mul_f32_e32 v50, v89, v90
	v_mul_f32_e32 v51, v113, v90
	v_fma_f32 v50, v113, v52, -v50
	v_fmac_f32_e32 v51, v89, v52
	v_mov_b32_e32 v52, v188
	v_mov_b32_e32 v90, v189
	v_mad_u64_u32 v[48:49], s[0:1], s54, v112, v[36:37]
	v_add_f32_e32 v50, v50, v91
	v_add_f32_e32 v51, v51, v114
	v_cvt_pk_bf16_f32 v91, v50, v53
	global_store_short v[48:49], v91, off
	v_cvt_pk_bf16_f32 v91, v51, v53
	global_store_short v[48:49], v91, off offset:128
	v_mul_f32_e32 v48, v89, v51
	v_mul_f32_e32 v49, v113, v51
	v_fma_f32 v48, v113, v50, -v48
	v_fmac_f32_e32 v49, v89, v50
	v_mov_b32_e32 v50, v190
	v_mov_b32_e32 v51, v191
	v_mad_u64_u32 v[44:45], s[0:1], s34, v112, v[36:37]
	v_add_f32_e32 v48, v48, v52
	v_add_f32_e32 v49, v49, v90
	v_cvt_pk_bf16_f32 v52, v48, v53
	global_store_short v[44:45], v52, off
	v_cvt_pk_bf16_f32 v52, v49, v53
	global_store_short v[44:45], v52, off offset:128
	v_mul_f32_e32 v44, v89, v49
	v_fma_f32 v44, v113, v48, -v44
	v_add_f32_e32 v50, v44, v50
	v_mul_f32_e32 v44, v113, v49
	v_mov_b32_e32 v49, v192
	s_nop 0
	v_mov_b32_e32 v46, v193
	v_fmac_f32_e32 v44, v89, v48
	v_add_f32_e32 v48, v44, v51
	v_cvt_pk_bf16_f32 v47, v50, v53
	v_mad_u64_u32 v[44:45], s[0:1], s68, v112, v[36:37]
	global_store_short v[44:45], v47, off
	v_cvt_pk_bf16_f32 v47, v48, v53
	global_store_short v[44:45], v47, off offset:128
	v_mul_f32_e32 v44, v89, v48
	v_fma_f32 v44, v113, v50, -v44
	v_add_f32_e32 v47, v44, v49
	v_mul_f32_e32 v44, v113, v48
	v_mov_b32_e32 v48, v194
	v_mov_b32_e32 v49, v195
	v_fmac_f32_e32 v44, v89, v50
	v_add_f32_e32 v46, v44, v46
	v_cvt_pk_bf16_f32 v50, v47, v53
	v_mad_u64_u32 v[44:45], s[0:1], s72, v112, v[36:37]
	global_store_short v[44:45], v50, off
	v_cvt_pk_bf16_f32 v50, v46, v53
	global_store_short v[44:45], v50, off offset:128
	v_mul_f32_e32 v44, v89, v46
	v_fma_f32 v44, v113, v47, -v44
	v_add_f32_e32 v48, v44, v48
	v_mul_f32_e32 v44, v113, v46
	v_fmac_f32_e32 v44, v89, v47
	v_add_f32_e32 v46, v44, v49
	v_mov_b32_e32 v47, v196
	v_mov_b32_e32 v49, v197
	v_cvt_pk_bf16_f32 v50, v48, v53
	v_mad_u64_u32 v[44:45], s[0:1], s52, v112, v[36:37]
	global_store_short v[44:45], v50, off
	v_cvt_pk_bf16_f32 v50, v46, v53
	global_store_short v[44:45], v50, off offset:128
	v_mul_f32_e32 v44, v89, v46
	v_fma_f32 v44, v113, v48, -v44
	v_add_f32_e32 v47, v44, v47
	v_mul_f32_e32 v44, v113, v46
	v_fmac_f32_e32 v44, v89, v48
	v_add_f32_e32 v46, v44, v49
	v_mov_b32_e32 v48, v198
	v_mov_b32_e32 v49, v199
	v_cvt_pk_bf16_f32 v50, v47, v53
	v_mad_u64_u32 v[44:45], s[0:1], s62, v112, v[36:37]
	global_store_short v[44:45], v50, off
	v_cvt_pk_bf16_f32 v50, v46, v53
	global_store_short v[44:45], v50, off offset:128
	v_mul_f32_e32 v44, v89, v46
	v_fma_f32 v44, v113, v47, -v44
	v_add_f32_e32 v48, v44, v48
	v_mul_f32_e32 v44, v113, v46
	v_fmac_f32_e32 v44, v89, v47
	v_add_f32_e32 v46, v44, v49
	v_mov_b32_e32 v47, v200
	v_mov_b32_e32 v49, v201
	v_cvt_pk_bf16_f32 v50, v48, v53
	v_mad_u64_u32 v[44:45], s[0:1], s60, v112, v[36:37]
	global_store_short v[44:45], v50, off
	v_cvt_pk_bf16_f32 v50, v46, v53
	global_store_short v[44:45], v50, off offset:128
	v_mul_f32_e32 v44, v89, v46
	v_fma_f32 v44, v113, v48, -v44
	v_add_f32_e32 v47, v44, v47
	v_mul_f32_e32 v44, v113, v46
	v_fmac_f32_e32 v44, v89, v48
	v_add_f32_e32 v46, v44, v49
	v_mov_b32_e32 v48, v202
	v_mov_b32_e32 v49, v203
	v_cvt_pk_bf16_f32 v50, v47, v53
	v_mad_u64_u32 v[44:45], s[0:1], s36, v112, v[36:37]
	global_store_short v[44:45], v50, off
	v_cvt_pk_bf16_f32 v50, v46, v53
	global_store_short v[44:45], v50, off offset:128
	v_mul_f32_e32 v44, v89, v46
	v_mul_f32_e32 v45, v113, v46
	v_fma_f32 v44, v113, v47, -v44
	v_fmac_f32_e32 v45, v89, v47
	v_mov_b32_e32 v46, v204
	v_mov_b32_e32 v47, v205
	v_mad_u64_u32 v[42:43], s[0:1], s82, v112, v[36:37]
	v_add_f32_e32 v44, v44, v48
	v_add_f32_e32 v45, v45, v49
	v_cvt_pk_bf16_f32 v48, v44, v53
	global_store_short v[42:43], v48, off
	v_cvt_pk_bf16_f32 v48, v45, v53
	global_store_short v[42:43], v48, off offset:128
	v_mul_f32_e32 v42, v89, v45
	v_mul_f32_e32 v43, v113, v45
	v_fma_f32 v42, v113, v44, -v42
	v_fmac_f32_e32 v43, v89, v44
	v_mov_b32_e32 v44, v206
	v_mov_b32_e32 v45, v207
	v_add_f32_e32 v42, v42, v46
	v_add_f32_e32 v43, v43, v47
	v_cvt_pk_bf16_f32 v46, v42, v53
	v_mad_u64_u32 v[40:41], s[0:1], s20, v112, v[36:37]
	global_store_short v[40:41], v46, off
	v_cvt_pk_bf16_f32 v46, v43, v53
	global_store_short v[40:41], v46, off offset:128
	v_mul_f32_e32 v40, v89, v43
	v_mul_f32_e32 v41, v113, v43
	v_fma_f32 v40, v113, v42, -v40
	v_fmac_f32_e32 v41, v89, v42
; __device__ __forceinline__ unsigned short f2bf(float f) { return (unsigned short)(cvt_pk_bf16(f, 0.f) & 0xffffu); }
; __device__ void ssm_scan_item(const Params& p, int b, int g, LAS unsigned char* lds) {
;     ...
;     for (int n = w * 32; n < w * 32 + 32; ++n) { const float ar = SL[(size_t)n * 128 + lane], ai = SL[(size_t)n * 128 + 64 + lane];
;       UGs[(size_t)n * 384 + lane] = f2bf(sr); UGs[(size_t)n * 384 + 64 + lane] = f2bf(si);
;       const float nr = l16r * sr - l16i * si + ar, ni = l16r * si + l16i * sr + ai; sr = nr; si = ni; } }
	v_mov_b32_e32 v42, v208
	v_mov_b32_e32 v43, v209
	v_mad_u64_u32 v[38:39], s[0:1], s70, v112, v[36:37]
	s_movk_i32 s20, 0x300
	v_add_f32_e32 v40, v40, v44
	v_add_f32_e32 v41, v41, v45
	v_cvt_pk_bf16_f32 v44, v40, v53
	global_store_short v[38:39], v44, off
	v_cvt_pk_bf16_f32 v44, v41, v53
	global_store_short v[38:39], v44, off offset:128
	v_mul_f32_e32 v38, v89, v41
	v_mul_f32_e32 v39, v113, v41
	v_fma_f32 v38, v113, v40, -v38
	v_fmac_f32_e32 v39, v89, v40
	v_mov_b32_e32 v40, v210
	v_mov_b32_e32 v41, v211
	v_mad_u64_u32 v[34:35], s[0:1], s22, v112, v[36:37]
	v_add_f32_e32 v38, v38, v42
	v_add_f32_e32 v39, v39, v43
	v_cvt_pk_bf16_f32 v42, v38, v53
	global_store_short v[34:35], v42, off
	v_cvt_pk_bf16_f32 v42, v39, v53
	global_store_short v[34:35], v42, off offset:128
	v_mul_f32_e32 v34, v89, v39
	v_mul_f32_e32 v35, v113, v39
	v_fma_f32 v34, v113, v38, -v34
	v_fmac_f32_e32 v35, v89, v38
	v_mov_b32_e32 v38, v212
	v_mov_b32_e32 v39, v213
	v_mad_u64_u32 v[30:31], s[0:1], s42, v112, v[36:37]
	v_add_f32_e32 v34, v34, v40
	v_add_f32_e32 v35, v35, v41
	v_cvt_pk_bf16_f32 v40, v34, v53
	global_store_short v[30:31], v40, off
	v_cvt_pk_bf16_f32 v40, v35, v53
	global_store_short v[30:31], v40, off offset:128
	v_mul_f32_e32 v30, v89, v35
	v_mul_f32_e32 v31, v113, v35
	v_fma_f32 v30, v113, v34, -v30
	v_fmac_f32_e32 v31, v89, v34
	v_mov_b32_e32 v34, v214
	v_mov_b32_e32 v35, v215
	v_mad_u64_u32 v[24:25], s[0:1], s76, v112, v[36:37]
	v_add_f32_e32 v30, v30, v38
	v_add_f32_e32 v31, v31, v39
	v_cvt_pk_bf16_f32 v38, v30, v53
	global_store_short v[24:25], v38, off
	v_cvt_pk_bf16_f32 v38, v31, v53
	global_store_short v[24:25], v38, off offset:128
	v_mul_f32_e32 v24, v89, v31
	v_mul_f32_e32 v25, v113, v31
	v_fma_f32 v24, v113, v30, -v24
	v_fmac_f32_e32 v25, v89, v30
	v_mov_b32_e32 v30, v216
	v_mov_b32_e32 v31, v217
	v_mad_u64_u32 v[22:23], s[0:1], s28, v112, v[36:37]
	v_add_f32_e32 v24, v24, v34
	v_add_f32_e32 v25, v25, v35
	v_cvt_pk_bf16_f32 v34, v24, v53
	global_store_short v[22:23], v34, off
	v_cvt_pk_bf16_f32 v34, v25, v53
	global_store_short v[22:23], v34, off offset:128
	v_mul_f32_e32 v22, v89, v25
	v_mul_f32_e32 v23, v113, v25
	v_fma_f32 v22, v113, v24, -v22
	v_fmac_f32_e32 v23, v89, v24
	v_mov_b32_e32 v24, v218
	v_mov_b32_e32 v25, v219
	v_mad_u64_u32 v[18:19], s[0:1], s50, v112, v[36:37]
	v_add_f32_e32 v22, v22, v30
	v_add_f32_e32 v23, v23, v31
	v_cvt_pk_bf16_f32 v30, v22, v53
	global_store_short v[18:19], v30, off
	v_cvt_pk_bf16_f32 v30, v23, v53
	global_store_short v[18:19], v30, off offset:128
	v_mul_f32_e32 v18, v89, v23
	v_fma_f32 v18, v113, v22, -v18
	v_add_f32_e32 v24, v18, v24
	v_mul_f32_e32 v18, v113, v23
	v_fmac_f32_e32 v18, v89, v22
	v_add_f32_e32 v22, v18, v25
	v_mov_b32_e32 v23, v220
	v_mov_b32_e32 v25, v221
	v_cvt_pk_bf16_f32 v30, v24, v53
	v_mad_u64_u32 v[18:19], s[0:1], s80, v112, v[36:37]
	global_store_short v[18:19], v30, off
	v_cvt_pk_bf16_f32 v30, v22, v53
	global_store_short v[18:19], v30, off offset:128
	v_mul_f32_e32 v18, v89, v22
	v_fma_f32 v18, v113, v24, -v18
	v_add_f32_e32 v23, v18, v23
	v_mul_f32_e32 v18, v113, v22
	v_fmac_f32_e32 v18, v89, v24
	v_add_f32_e32 v22, v18, v25
	v_mov_b32_e32 v24, v222
	v_mov_b32_e32 v25, v223
	v_cvt_pk_bf16_f32 v28, v23, v53
	v_mad_u64_u32 v[18:19], s[0:1], s48, v112, v[36:37]
	global_store_short v[18:19], v28, off
	v_cvt_pk_bf16_f32 v28, v22, v53
	global_store_short v[18:19], v28, off offset:128
	v_mul_f32_e32 v18, v89, v22
	v_fma_f32 v18, v113, v23, -v18
	v_add_f32_e32 v24, v18, v24
	v_mul_f32_e32 v18, v113, v22
	v_fmac_f32_e32 v18, v89, v23
	v_add_f32_e32 v22, v18, v25
	v_mov_b32_e32 v23, v224
	v_mov_b32_e32 v25, v225
	v_cvt_pk_bf16_f32 v26, v24, v53
	v_mad_u64_u32 v[18:19], s[0:1], s78, v112, v[36:37]
	global_store_short v[18:19], v26, off
	v_cvt_pk_bf16_f32 v26, v22, v53
	global_store_short v[18:19], v26, off offset:128
	v_mul_f32_e32 v18, v89, v22
	v_fma_f32 v18, v113, v24, -v18
	v_add_f32_e32 v23, v18, v23
	v_mul_f32_e32 v18, v113, v22
	v_fmac_f32_e32 v18, v89, v24
	v_mov_b32_e32 v24, v226
	s_nop 0
	v_mov_b32_e32 v20, v227
	v_add_f32_e32 v22, v18, v25
	v_cvt_pk_bf16_f32 v21, v23, v53
	v_mad_u64_u32 v[18:19], s[0:1], s30, v112, v[36:37]
	global_store_short v[18:19], v21, off
	v_cvt_pk_bf16_f32 v21, v22, v53
	global_store_short v[18:19], v21, off offset:128
	v_mul_f32_e32 v19, v113, v22
	v_fmac_f32_e32 v19, v89, v23
; __device__ __forceinline__ unsigned short f2bf(float f) { return (unsigned short)(cvt_pk_bf16(f, 0.f) & 0xffffu); }
; __device__ void ssm_scan_item(const Params& p, int b, int g, LAS unsigned char* lds) {
;     ...
;     for (int n = w * 32; n < w * 32 + 32; ++n) { const float ar = SL[(size_t)n * 128 + lane], ai = SL[(size_t)n * 128 + 64 + lane];
;       UGs[(size_t)n * 384 + lane] = f2bf(sr); UGs[(size_t)n * 384 + 64 + lane] = f2bf(si);
;       const float nr = l16r * sr - l16i * si + ar, ni = l16r * si + l16i * sr + ai; sr = nr; si = ni; } }
;   __syncthreads();
	v_mul_f32_e32 v18, v89, v22
	v_readlane_b32 s0, v246, 53
	v_fma_f32 v18, v113, v23, -v18
	v_readlane_b32 s1, v246, 54
	v_add_f32_e32 v18, v18, v24
	v_add_f32_e32 v19, v19, v20
	v_mov_b32_e32 v20, v228
	v_mov_b32_e32 v21, v229
	v_cvt_pk_bf16_f32 v22, v18, v53
	v_mad_u64_u32 v[16:17], s[0:1], s0, v112, v[36:37]
	global_store_short v[16:17], v22, off
	v_cvt_pk_bf16_f32 v22, v19, v53
	global_store_short v[16:17], v22, off offset:128
	v_mul_f32_e32 v16, v89, v19
	v_mul_f32_e32 v17, v113, v19
	v_fma_f32 v16, v113, v18, -v16
	v_fmac_f32_e32 v17, v89, v18
	v_mov_b32_e32 v18, v230
	v_mov_b32_e32 v19, v231
	v_readlane_b32 s0, v246, 55
	v_readlane_b32 s1, v246, 56
	v_add_f32_e32 v16, v16, v20
	v_add_f32_e32 v17, v17, v21
	v_cvt_pk_bf16_f32 v20, v16, v53
	v_mad_u64_u32 v[14:15], s[0:1], s0, v112, v[36:37]
	global_store_short v[14:15], v20, off
	v_cvt_pk_bf16_f32 v20, v17, v53
	global_store_short v[14:15], v20, off offset:128
	v_mul_f32_e32 v14, v89, v17
	v_mul_f32_e32 v15, v113, v17
	v_fma_f32 v14, v113, v16, -v14
	v_fmac_f32_e32 v15, v89, v16
	v_mov_b32_e32 v16, v232
	v_mov_b32_e32 v17, v233
	v_readlane_b32 s0, v246, 57
	v_readlane_b32 s1, v246, 58
	v_add_f32_e32 v14, v14, v18
	v_add_f32_e32 v15, v15, v19
	v_cvt_pk_bf16_f32 v18, v14, v53
	v_mad_u64_u32 v[12:13], s[0:1], s0, v112, v[36:37]
	global_store_short v[12:13], v18, off
	v_cvt_pk_bf16_f32 v18, v15, v53
	global_store_short v[12:13], v18, off offset:128
	v_mul_f32_e32 v12, v89, v15
	v_mul_f32_e32 v13, v113, v15
	v_fma_f32 v12, v113, v14, -v12
	v_fmac_f32_e32 v13, v89, v14
	v_mov_b32_e32 v14, v234
	v_mov_b32_e32 v15, v235
	v_readlane_b32 s0, v246, 59
	v_readlane_b32 s1, v246, 60
	v_add_f32_e32 v12, v12, v16
	v_add_f32_e32 v13, v13, v17
	v_cvt_pk_bf16_f32 v16, v12, v53
	v_mad_u64_u32 v[10:11], s[0:1], s0, v112, v[36:37]
	global_store_short v[10:11], v16, off
	v_cvt_pk_bf16_f32 v16, v13, v53
	global_store_short v[10:11], v16, off offset:128
	v_mul_f32_e32 v10, v89, v13
	v_mul_f32_e32 v11, v113, v13
	v_fma_f32 v10, v113, v12, -v10
	v_fmac_f32_e32 v11, v89, v12
	v_mov_b32_e32 v12, v236
	v_mov_b32_e32 v13, v237
	v_mad_u64_u32 v[8:9], s[0:1], s44, v112, v[36:37]
	v_add_f32_e32 v10, v10, v14
	v_add_f32_e32 v11, v11, v15
	v_cvt_pk_bf16_f32 v14, v10, v53
	global_store_short v[8:9], v14, off
	v_cvt_pk_bf16_f32 v14, v11, v53
	global_store_short v[8:9], v14, off offset:128
	v_mul_f32_e32 v8, v89, v11
	v_mul_f32_e32 v9, v113, v11
	v_fma_f32 v8, v113, v10, -v8
	v_fmac_f32_e32 v9, v89, v10
	v_mov_b32_e32 v10, v238
	v_mov_b32_e32 v11, v239
	v_mad_u64_u32 v[6:7], s[0:1], s96, v112, v[36:37]
	v_add_f32_e32 v8, v8, v12
	v_add_f32_e32 v9, v9, v13
	v_cvt_pk_bf16_f32 v12, v8, v53
	global_store_short v[6:7], v12, off
	v_cvt_pk_bf16_f32 v12, v9, v53
	global_store_short v[6:7], v12, off offset:128
	v_mul_f32_e32 v6, v89, v9
	v_mul_f32_e32 v7, v113, v9
	v_fma_f32 v6, v113, v8, -v6
	v_fmac_f32_e32 v7, v89, v8
	v_mov_b32_e32 v8, v240
	v_mov_b32_e32 v9, v241
	v_mad_u64_u32 v[4:5], s[0:1], s94, v112, v[36:37]
	v_add_f32_e32 v6, v6, v10
	v_add_f32_e32 v7, v7, v11
	v_cvt_pk_bf16_f32 v10, v6, v53
	global_store_short v[4:5], v10, off
	v_cvt_pk_bf16_f32 v10, v7, v53
	global_store_short v[4:5], v10, off offset:128
	v_mul_f32_e32 v4, v89, v7
	v_mul_f32_e32 v5, v113, v7
	v_fma_f32 v4, v113, v6, -v4
	v_fmac_f32_e32 v5, v89, v6
	v_mov_b32_e32 v6, v242
	v_mov_b32_e32 v7, v243
	v_mad_u64_u32 v[2:3], s[0:1], s92, v112, v[36:37]
	v_add_f32_e32 v4, v4, v8
	v_add_f32_e32 v5, v5, v9
	v_cvt_pk_bf16_f32 v8, v4, v53
	global_store_short v[2:3], v8, off
	v_cvt_pk_bf16_f32 v8, v5, v53
	global_store_short v[2:3], v8, off offset:128
	v_mul_f32_e32 v2, v89, v5
	v_mul_f32_e32 v3, v113, v5
	v_fma_f32 v2, v113, v4, -v2
	v_fmac_f32_e32 v3, v89, v4
	v_mov_b32_e32 v4, v244
	v_mov_b32_e32 v5, v245
	v_mad_u64_u32 v[0:1], s[0:1], s24, v112, v[36:37]
	v_add_f32_e32 v2, v2, v6
	v_add_f32_e32 v3, v3, v7
	v_cvt_pk_bf16_f32 v6, v2, v53
	global_store_short v[0:1], v6, off
	v_cvt_pk_bf16_f32 v6, v3, v53
	global_store_short v[0:1], v6, off offset:128
	v_mul_f32_e32 v0, v89, v3
	v_fma_f32 v0, v113, v2, -v0
	v_mul_f32_e32 v1, v113, v3
	v_fmac_f32_e32 v1, v89, v2
	v_add_f32_e32 v0, v0, v4
	v_add_f32_e32 v2, v1, v5
	v_cvt_pk_bf16_f32 v3, v0, v53
	v_mad_u64_u32 v[0:1], s[0:1], s26, v112, v[36:37]
	global_store_short v[0:1], v3, off
	v_cvt_pk_bf16_f32 v2, v2, v53
	global_store_short v[0:1], v2, off offset:128
	s_barrier

; __device__ __forceinline__ void lam_pow(const Params& p, int g, int pp, float e, float& re, float& im) {
;   const float dt = __expf(p.in[17][g]), lr = p.in[15][g * 64 + pp], li = p.in[16][g * 64 + pp];
;   const float mag = expf(lr * dt * e); float sn, cs; sincosf(li * dt * e, &sn, &cs); re = mag * cs; im = mag * sn; }
; __device__ void ssm_scan_item(const Params& p, int b, int g, LAS unsigned char* lds) {
;     ...
;   float l16r, l16i; lam_pow(p, g, lane, 16.f, l16r, l16i);
;   { float sr = 0.f, si = 0.f;
; #pragma unroll 32
;     for (int n = w * 32; n < w * 32 + 32; ++n) { const float ar = SL[(size_t)n * 128 + lane], ai = SL[(size_t)n * 128 + 64 + lane]; const float nr = l16r * sr - l16i * si + ar, ni = l16r * si + l16i * sr + ai; sr = nr; si = ni; }
.LBB0_770:
	s_andn2_saveexec_b64 s[0:1], s[4:5]
	v_mul_f32_e64 v4, |v0|, s65
	v_rndne_f32_e32 v6, v4
	v_cvt_i32_f32_e32 v5, v6
	v_fma_f32 v4, v6, s66, |v0|
	v_fmac_f32_e32 v4, 0xb3a22168, v6
	v_fmac_f32_e32 v4, 0xa7c234c4, v6
	s_or_b64 exec, exec, s[0:1]
	s_waitcnt vmcnt(0)
	v_mul_f32_e32 v2, v2, v3
	v_mul_f32_e32 v2, 0x41800000, v2
	v_mul_f32_e32 v3, 0x3fb8aa3b, v2
	v_fma_f32 v6, v2, s3, -v3
	v_rndne_f32_e32 v7, v3
	v_fmac_f32_e32 v6, 0x32a5705f, v2
	v_sub_f32_e32 v3, v3, v7
	v_add_f32_e32 v3, v3, v6
	v_exp_f32_e32 v3, v3
	v_cvt_i32_f32_e32 v6, v7
	v_cmp_ngt_f32_e32 vcc, s67, v2
	s_lshl_b32 s1, s58, 2
	s_and_b32 s1, s1, 0xffffff00
	v_ldexp_f32 v3, v3, v6
	v_cndmask_b32_e32 v3, 0, v3, vcc
	v_cmp_nlt_f32_e32 vcc, s40, v2
	s_lshr_b32 s12, s59, 6
	s_lshl_b32 s0, s6, 11
	v_cndmask_b32_e32 v2, v110, v3, vcc
	v_mul_f32_e32 v3, v4, v4
	v_fmamk_f32 v6, v3, 0xb94c1982, v106
	v_fmaak_f32 v6, v3, v6, 0xbe2aaa9d
	v_mul_f32_e32 v6, v3, v6
	v_fmac_f32_e32 v4, v4, v6
	v_fmamk_f32 v6, v3, 0x37d75334, v107
	v_fmaak_f32 v6, v3, v6, 0x3d2aabf7
	v_fmaak_f32 v6, v3, v6, 0xbf000004
	s_ashr_i32 s4, s1, 31
	v_fma_f32 v3, v3, v6, 1.0
	v_lshlrev_b32_e32 v6, 30, v5
	v_and_b32_e32 v5, 1, v5
	s_add_u32 s74, s0, s1
	v_cmp_eq_u32_e32 vcc, 0, v5
	s_addc_u32 s75, 0, s4
	v_xor_b32_e32 v1, v1, v0
	v_cndmask_b32_e32 v5, v3, v4, vcc
	v_xor_b32_e32 v4, 0x80000000, v4
	s_lshl_b64 s[0:1], s[74:75], 9
	v_and_b32_e32 v7, 0x80000000, v6
	v_xor_b32_e32 v1, v1, v5
	v_cndmask_b32_e32 v3, v4, v3, vcc
	s_lshl_b32 s56, s12, 5
	v_xor_b32_e32 v1, v1, v7
	v_bitop3_b32 v3, v3, v6, s41 bitop3:0x78
	v_cmp_class_f32_e64 vcc, v0, s64
	v_lshl_add_u64 v[36:37], v[82:83], 0, s[0:1]
	s_lshl_b64 s[0:1], s[56:57], 9
	v_cndmask_b32_e32 v0, v111, v3, vcc
	v_cndmask_b32_e32 v1, v111, v1, vcc
	v_lshl_add_u64 v[90:91], v[36:37], 0, s[0:1]
	v_mul_f32_e32 v113, v2, v0
	v_mul_f32_e32 v89, v2, v1
	s_mov_b64 s[0:1], 0x1000
	v_lshl_add_u64 v[162:163], v[90:91], 0, s[0:1]
	v_lshl_add_u64 v[164:165], v[162:163], 0, s[0:1]
	v_lshl_add_u64 v[166:167], v[164:165], 0, s[0:1]
	global_load_dword v184, v[90:91], off
	global_load_dword v185, v[90:91], off offset:256
	global_load_dword v186, v[90:91], off offset:512
	global_load_dword v187, v[90:91], off offset:768
	global_load_dword v188, v[90:91], off offset:1024
	global_load_dword v189, v[90:91], off offset:1280
	global_load_dword v190, v[90:91], off offset:1536
	global_load_dword v191, v[90:91], off offset:1792
	global_load_dword v192, v[90:91], off offset:2048
	global_load_dword v193, v[90:91], off offset:2304
	global_load_dword v194, v[90:91], off offset:2560
	global_load_dword v195, v[90:91], off offset:2816
	global_load_dword v196, v[90:91], off offset:3072
	global_load_dword v197, v[90:91], off offset:3328
	global_load_dword v198, v[90:91], off offset:3584
	global_load_dword v199, v[90:91], off offset:3840
	global_load_dword v200, v[162:163], off
	global_load_dword v201, v[162:163], off offset:256
	global_load_dword v202, v[162:163], off offset:512
	global_load_dword v203, v[162:163], off offset:768
	global_load_dword v204, v[162:163], off offset:1024
	global_load_dword v205, v[162:163], off offset:1280
	global_load_dword v206, v[162:163], off offset:1536
	global_load_dword v207, v[162:163], off offset:1792
	global_load_dword v208, v[162:163], off offset:2048
	global_load_dword v209, v[162:163], off offset:2304
	global_load_dword v210, v[162:163], off offset:2560
	global_load_dword v211, v[162:163], off offset:2816
	global_load_dword v212, v[162:163], off offset:3072
	global_load_dword v213, v[162:163], off offset:3328
	global_load_dword v214, v[162:163], off offset:3584
	global_load_dword v215, v[162:163], off offset:3840
	global_load_dword v216, v[164:165], off
	global_load_dword v217, v[164:165], off offset:256
	global_load_dword v218, v[164:165], off offset:512
	global_load_dword v219, v[164:165], off offset:768
	global_load_dword v220, v[164:165], off offset:1024
	global_load_dword v221, v[164:165], off offset:1280
	global_load_dword v222, v[164:165], off offset:1536
	global_load_dword v223, v[164:165], off offset:1792
	global_load_dword v224, v[164:165], off offset:2048
	global_load_dword v225, v[164:165], off offset:2304
	global_load_dword v226, v[164:165], off offset:2560
	global_load_dword v227, v[164:165], off offset:2816
	global_load_dword v228, v[164:165], off offset:3072
	global_load_dword v229, v[164:165], off offset:3328
	global_load_dword v230, v[164:165], off offset:3584
	global_load_dword v231, v[164:165], off offset:3840
	global_load_dword v232, v[166:167], off
	global_load_dword v233, v[166:167], off offset:256
	global_load_dword v234, v[166:167], off offset:512
	global_load_dword v235, v[166:167], off offset:768
	global_load_dword v236, v[166:167], off offset:1024
	global_load_dword v237, v[166:167], off offset:1280
	global_load_dword v238, v[166:167], off offset:1536
	global_load_dword v239, v[166:167], off offset:1792
	global_load_dword v240, v[166:167], off offset:2048
	global_load_dword v241, v[166:167], off offset:2304
	global_load_dword v242, v[166:167], off offset:2560
	global_load_dword v243, v[166:167], off offset:2816
	global_load_dword v244, v[166:167], off offset:3072
	global_load_dword v245, v[166:167], off offset:3328
	global_load_dword v160, v[166:167], off offset:3584
	global_load_dword v161, v[166:167], off offset:3840
	s_waitcnt vmcnt(62)
; __device__ void ssm_scan_item(const Params& p, int b, int g, LAS unsigned char* lds) {
;     ...
;   { float sr = 0.f, si = 0.f;
; #pragma unroll 32
;     for (int n = w * 32; n < w * 32 + 32; ++n) { const float ar = SL[(size_t)n * 128 + lane], ai = SL[(size_t)n * 128 + 64 + lane]; const float nr = l16r * sr - l16i * si + ar, ni = l16r * si + l16i * sr + ai; sr = nr; si = ni; }
;     segend[w * 128 + lane] = sr; segend[w * 128 + 64 + lane] = si; }
	v_mov_b32_e32 v0, v184
	v_mov_b32_e32 v1, v185
	s_or_b32 s46, s56, 1
	s_mov_b32 s47, s57
	v_mul_f32_e32 v2, 0, v89
	s_lshl_b64 s[0:1], s[46:47], 9
	v_fma_f32 v3, v113, 0, -v2
	v_fmac_f32_e32 v2, 0, v113
	v_lshl_add_u64 v[50:51], v[36:37], 0, s[0:1]
	s_or_b32 s54, s56, 2
	s_mov_b32 s55, s57
	s_lshl_b64 s[0:1], s[54:55], 9
	v_lshl_add_u64 v[48:49], v[36:37], 0, s[0:1]
	s_or_b32 s34, s56, 3
	s_mov_b32 s35, s57
	s_lshl_b64 s[0:1], s[34:35], 9
	v_lshl_add_u64 v[44:45], v[36:37], 0, s[0:1]
	s_or_b32 s68, s56, 4
	s_mov_b32 s69, s57
	s_lshl_b64 s[0:1], s[68:69], 9
	v_lshl_add_u64 v[46:47], v[36:37], 0, s[0:1]
	s_or_b32 s72, s56, 5
	s_mov_b32 s73, s57
	s_lshl_b64 s[0:1], s[72:73], 9
	v_lshl_add_u64 v[98:99], v[36:37], 0, s[0:1]
	s_or_b32 s52, s56, 6
	s_mov_b32 s53, s57
	s_lshl_b64 s[0:1], s[52:53], 9
	v_lshl_add_u64 v[100:101], v[36:37], 0, s[0:1]
	s_or_b32 s62, s56, 7
	s_mov_b32 s63, s57
	s_lshl_b64 s[0:1], s[62:63], 9
	v_lshl_add_u64 v[96:97], v[36:37], 0, s[0:1]
	s_or_b32 s60, s56, 8
	s_mov_b32 s61, s57
	s_lshl_b64 s[0:1], s[60:61], 9
	v_lshl_add_u64 v[94:95], v[36:37], 0, s[0:1]
	s_or_b32 s36, s56, 9
	s_mov_b32 s37, s57
	s_lshl_b64 s[0:1], s[36:37], 9
	v_lshl_add_u64 v[92:93], v[36:37], 0, s[0:1]
	s_or_b32 s82, s56, 10
	s_mov_b32 s83, s57
	s_lshl_b64 s[0:1], s[82:83], 9
	v_lshl_add_u64 v[42:43], v[36:37], 0, s[0:1]
	s_or_b32 s20, s56, 11
	s_mov_b32 s21, s57
	s_lshl_b64 s[0:1], s[20:21], 9
	v_lshl_add_u64 v[40:41], v[36:37], 0, s[0:1]
	s_or_b32 s70, s56, 12
	s_mov_b32 s71, s57
	s_lshl_b64 s[0:1], s[70:71], 9
	v_lshl_add_u64 v[38:39], v[36:37], 0, s[0:1]
	s_or_b32 s22, s56, 13
	s_mov_b32 s23, s57
	s_lshl_b64 s[0:1], s[22:23], 9
	v_lshl_add_u64 v[34:35], v[36:37], 0, s[0:1]
	s_or_b32 s42, s56, 14
	s_mov_b32 s43, s57
	s_lshl_b64 s[0:1], s[42:43], 9
	v_lshl_add_u64 v[30:31], v[36:37], 0, s[0:1]
	s_or_b32 s76, s56, 15
	s_mov_b32 s77, s57
	s_lshl_b64 s[0:1], s[76:77], 9
	v_lshl_add_u64 v[24:25], v[36:37], 0, s[0:1]
	s_or_b32 s28, s56, 16
	s_mov_b32 s29, s57
	s_lshl_b64 s[0:1], s[28:29], 9
	v_lshl_add_u64 v[22:23], v[36:37], 0, s[0:1]
	s_or_b32 s50, s56, 17
	s_mov_b32 s51, s57
	s_lshl_b64 s[0:1], s[50:51], 9
	v_lshl_add_u64 v[18:19], v[36:37], 0, s[0:1]
	s_or_b32 s80, s56, 18
	s_mov_b32 s81, s57
	s_lshl_b64 s[0:1], s[80:81], 9
	v_lshl_add_u64 v[32:33], v[36:37], 0, s[0:1]
	s_or_b32 s48, s56, 19
	s_mov_b32 s49, s57
	s_lshl_b64 s[0:1], s[48:49], 9
	v_add_f32_e32 v0, v0, v3
	v_add_f32_e32 v1, v1, v2
	s_waitcnt vmcnt(60)
	v_mov_b32_e32 v2, v186
	v_mov_b32_e32 v3, v187
	v_mul_f32_e32 v4, v89, v1
	v_fma_f32 v4, v113, v0, -v4
	v_mul_f32_e32 v0, v89, v0
	v_fmac_f32_e32 v0, v113, v1
	v_lshl_add_u64 v[28:29], v[36:37], 0, s[0:1]
	s_or_b32 s78, s56, 20
	s_mov_b32 s79, s57
	s_lshl_b64 s[0:1], s[78:79], 9
	v_lshl_add_u64 v[26:27], v[36:37], 0, s[0:1]
	s_or_b32 s30, s56, 21
	s_mov_b32 s31, s57
	s_lshl_b64 s[0:1], s[30:31], 9
	v_lshl_add_u64 v[20:21], v[36:37], 0, s[0:1]
	s_or_b32 s0, s56, 22
	s_mov_b32 s1, s57
	s_mov_b32 s4, s0
	s_lshl_b64 s[0:1], s[0:1], 9
	v_lshl_add_u64 v[16:17], v[36:37], 0, s[0:1]
	v_writelane_b32 v246, s4, 53
	s_or_b32 s0, s56, 23
	s_mov_b32 s1, s57
	v_writelane_b32 v246, s5, 54
	s_mov_b32 s4, s0
	s_lshl_b64 s[0:1], s[0:1], 9
	v_lshl_add_u64 v[14:15], v[36:37], 0, s[0:1]
	v_writelane_b32 v246, s4, 55
	s_or_b32 s0, s56, 24
	s_mov_b32 s1, s57
	v_writelane_b32 v246, s5, 56
	s_mov_b32 s4, s0
	s_lshl_b64 s[0:1], s[0:1], 9
	v_lshl_add_u64 v[12:13], v[36:37], 0, s[0:1]
	v_writelane_b32 v246, s4, 57
	s_or_b32 s0, s56, 25
	s_mov_b32 s1, s57
	v_writelane_b32 v246, s5, 58
	s_mov_b32 s4, s0
	s_lshl_b64 s[0:1], s[0:1], 9
	v_lshl_add_u64 v[10:11], v[36:37], 0, s[0:1]
	s_or_b32 s44, s56, 26
	s_mov_b32 s45, s57
	s_lshl_b64 s[0:1], s[44:45], 9
	v_lshl_add_u64 v[8:9], v[36:37], 0, s[0:1]
	s_or_b32 s96, s56, 27
	s_mov_b32 s97, s57
	s_lshl_b64 s[0:1], s[96:97], 9
	v_lshl_add_u64 v[6:7], v[36:37], 0, s[0:1]
	s_or_b32 s94, s56, 28
	s_mov_b32 s95, s57
	s_lshl_b64 s[0:1], s[94:95], 9
	s_or_b32 s92, s56, 29
	s_mov_b32 s93, s57
	s_or_b32 s24, s56, 30
	s_mov_b32 s25, s57
	s_or_b32 s26, s56, 31
	s_mov_b32 s27, s57
	v_writelane_b32 v246, s4, 59
	v_add_f32_e32 v2, v2, v4
	v_add_f32_e32 v0, v3, v0
	s_waitcnt vmcnt(58)
	v_mov_b32_e32 v1, v188
	v_mov_b32_e32 v3, v189
	v_mul_f32_e32 v4, v89, v0
	v_fma_f32 v4, v113, v2, -v4
	v_mul_f32_e32 v2, v89, v2
	v_fmac_f32_e32 v2, v113, v0
	v_writelane_b32 v246, s5, 60
	v_add_f32_e32 v1, v1, v4
	v_add_f32_e32 v0, v3, v2
	s_waitcnt vmcnt(56)
	v_mov_b32_e32 v2, v190
	v_mov_b32_e32 v3, v191
	v_mul_f32_e32 v4, v89, v0
	v_fma_f32 v4, v113, v1, -v4
	v_mul_f32_e32 v1, v89, v1
	v_fmac_f32_e32 v1, v113, v0
	v_add_f32_e32 v2, v2, v4
	v_add_f32_e32 v0, v3, v1
	s_waitcnt vmcnt(54)
	v_mov_b32_e32 v1, v192
	v_mov_b32_e32 v3, v193
	v_mul_f32_e32 v4, v89, v0
	v_fma_f32 v4, v113, v2, -v4
	v_mul_f32_e32 v2, v89, v2
	v_fmac_f32_e32 v2, v113, v0
	v_add_f32_e32 v1, v1, v4
	v_add_f32_e32 v0, v3, v2
	s_waitcnt vmcnt(52)
	v_mov_b32_e32 v2, v194
	v_mov_b32_e32 v3, v195
	v_mul_f32_e32 v4, v89, v0
	v_fma_f32 v4, v113, v1, -v4
	v_mul_f32_e32 v1, v89, v1
	v_fmac_f32_e32 v1, v113, v0
	v_add_f32_e32 v2, v2, v4
	v_add_f32_e32 v0, v3, v1
	s_waitcnt vmcnt(50)
	v_mov_b32_e32 v1, v196
	v_mov_b32_e32 v3, v197
	v_mul_f32_e32 v4, v89, v0
	v_fma_f32 v4, v113, v2, -v4
	v_mul_f32_e32 v2, v89, v2
	v_fmac_f32_e32 v2, v113, v0
	v_add_f32_e32 v1, v1, v4
	v_add_f32_e32 v0, v3, v2
	s_waitcnt vmcnt(48)
	v_mov_b32_e32 v2, v198
	v_mov_b32_e32 v3, v199
	v_mul_f32_e32 v4, v89, v0
	v_fma_f32 v4, v113, v1, -v4
	v_mul_f32_e32 v1, v89, v1
	v_fmac_f32_e32 v1, v113, v0
	v_add_f32_e32 v2, v2, v4
	v_add_f32_e32 v0, v3, v1
	s_waitcnt vmcnt(46)
; __device__ void ssm_scan_item(const Params& p, int b, int g, LAS unsigned char* lds) {
;     ...
;   { float sr = 0.f, si = 0.f;
; #pragma unroll 32
;     for (int n = w * 32; n < w * 32 + 32; ++n) { const float ar = SL[(size_t)n * 128 + lane], ai = SL[(size_t)n * 128 + 64 + lane]; const float nr = l16r * sr - l16i * si + ar, ni = l16r * si + l16i * sr + ai; sr = nr; si = ni; }
;     segend[w * 128 + lane] = sr; segend[w * 128 + 64 + lane] = si; }
;   __syncthreads();
	v_mov_b32_e32 v1, v200
	v_mov_b32_e32 v3, v201
	v_mul_f32_e32 v4, v89, v0
	v_fma_f32 v4, v113, v2, -v4
	v_mul_f32_e32 v2, v89, v2
	v_fmac_f32_e32 v2, v113, v0
	v_add_f32_e32 v1, v1, v4
	v_add_f32_e32 v0, v3, v2
	s_waitcnt vmcnt(44)
	v_mov_b32_e32 v2, v202
	v_mov_b32_e32 v3, v203
	v_mul_f32_e32 v4, v89, v0
	v_fma_f32 v4, v113, v1, -v4
	v_mul_f32_e32 v1, v89, v1
	v_fmac_f32_e32 v1, v113, v0
	v_add_f32_e32 v2, v2, v4
	v_add_f32_e32 v0, v3, v1
	s_waitcnt vmcnt(42)
	v_mov_b32_e32 v1, v204
	v_mov_b32_e32 v3, v205
	v_mul_f32_e32 v4, v89, v0
	v_fma_f32 v4, v113, v2, -v4
	v_mul_f32_e32 v2, v89, v2
	v_fmac_f32_e32 v2, v113, v0
	v_add_f32_e32 v1, v1, v4
	v_add_f32_e32 v0, v3, v2
	s_waitcnt vmcnt(40)
	v_mov_b32_e32 v2, v206
	v_mov_b32_e32 v3, v207
	v_mul_f32_e32 v4, v89, v0
	v_fma_f32 v4, v113, v1, -v4
	v_mul_f32_e32 v1, v89, v1
	v_fmac_f32_e32 v1, v113, v0
	v_add_f32_e32 v2, v2, v4
	v_add_f32_e32 v0, v3, v1
	s_waitcnt vmcnt(38)
	v_mov_b32_e32 v1, v208
	v_mov_b32_e32 v3, v209
	v_mul_f32_e32 v4, v89, v0
	v_fma_f32 v4, v113, v2, -v4
	v_mul_f32_e32 v2, v89, v2
	v_fmac_f32_e32 v2, v113, v0
	v_add_f32_e32 v1, v1, v4
	v_add_f32_e32 v0, v3, v2
	s_waitcnt vmcnt(36)
	v_mov_b32_e32 v2, v210
	v_mov_b32_e32 v3, v211
	v_mul_f32_e32 v4, v89, v0
	v_fma_f32 v4, v113, v1, -v4
	v_mul_f32_e32 v1, v89, v1
	v_fmac_f32_e32 v1, v113, v0
	v_add_f32_e32 v2, v2, v4
	v_add_f32_e32 v0, v3, v1
	s_waitcnt vmcnt(34)
	v_mov_b32_e32 v1, v212
	v_mov_b32_e32 v3, v213
	v_mul_f32_e32 v4, v89, v0
	v_fma_f32 v4, v113, v2, -v4
	v_mul_f32_e32 v2, v89, v2
	v_fmac_f32_e32 v2, v113, v0
	v_add_f32_e32 v1, v1, v4
	v_add_f32_e32 v0, v3, v2
	s_waitcnt vmcnt(32)
	v_mov_b32_e32 v2, v214
	v_mov_b32_e32 v3, v215
	v_mul_f32_e32 v4, v89, v0
	v_fma_f32 v4, v113, v1, -v4
	v_mul_f32_e32 v1, v89, v1
	v_fmac_f32_e32 v1, v113, v0
	v_add_f32_e32 v2, v2, v4
	v_add_f32_e32 v0, v3, v1
	s_waitcnt vmcnt(30)
	v_mov_b32_e32 v1, v216
	v_mov_b32_e32 v3, v217
	v_mul_f32_e32 v4, v89, v0
	v_fma_f32 v4, v113, v2, -v4
	v_mul_f32_e32 v2, v89, v2
	v_fmac_f32_e32 v2, v113, v0
	v_add_f32_e32 v1, v1, v4
	v_add_f32_e32 v0, v3, v2
	s_waitcnt vmcnt(28)
	v_mov_b32_e32 v2, v218
	v_mov_b32_e32 v3, v219
	v_mul_f32_e32 v4, v89, v0
	v_fma_f32 v4, v113, v1, -v4
	v_mul_f32_e32 v1, v89, v1
	v_fmac_f32_e32 v1, v113, v0
	v_add_f32_e32 v2, v2, v4
	v_add_f32_e32 v0, v3, v1
	s_waitcnt vmcnt(26)
	v_mov_b32_e32 v1, v220
	v_mov_b32_e32 v3, v221
	v_mul_f32_e32 v4, v89, v0
	v_fma_f32 v4, v113, v2, -v4
	v_mul_f32_e32 v2, v89, v2
	v_fmac_f32_e32 v2, v113, v0
	v_add_f32_e32 v1, v1, v4
	v_add_f32_e32 v0, v3, v2
	s_waitcnt vmcnt(24)
	v_mov_b32_e32 v2, v222
	v_mov_b32_e32 v3, v223
	v_mul_f32_e32 v4, v89, v0
	v_fma_f32 v4, v113, v1, -v4
	v_mul_f32_e32 v1, v89, v1
	v_fmac_f32_e32 v1, v113, v0
	v_add_f32_e32 v2, v2, v4
	v_add_f32_e32 v0, v3, v1
	s_waitcnt vmcnt(22)
	v_mov_b32_e32 v1, v224
	v_mov_b32_e32 v3, v225
	v_mul_f32_e32 v4, v89, v0
	v_fma_f32 v4, v113, v2, -v4
	v_mul_f32_e32 v2, v89, v2
	v_fmac_f32_e32 v2, v113, v0
	v_add_f32_e32 v1, v1, v4
	v_add_f32_e32 v0, v3, v2
	s_waitcnt vmcnt(20)
	v_mov_b32_e32 v2, v226
	v_mov_b32_e32 v3, v227
	v_mul_f32_e32 v4, v89, v0
	v_fma_f32 v4, v113, v1, -v4
	v_mul_f32_e32 v1, v89, v1
	v_fmac_f32_e32 v1, v113, v0
	v_add_f32_e32 v2, v2, v4
	v_add_f32_e32 v0, v3, v1
	s_waitcnt vmcnt(18)
	v_mov_b32_e32 v1, v228
	v_mov_b32_e32 v3, v229
	v_mul_f32_e32 v4, v89, v0
	v_fma_f32 v4, v113, v2, -v4
	v_mul_f32_e32 v2, v89, v2
	v_fmac_f32_e32 v2, v113, v0
	v_add_f32_e32 v1, v1, v4
	v_add_f32_e32 v0, v3, v2
	s_waitcnt vmcnt(16)
	v_mov_b32_e32 v2, v230
	v_mov_b32_e32 v3, v231
	v_mul_f32_e32 v4, v89, v0
	v_fma_f32 v4, v113, v1, -v4
	v_mul_f32_e32 v1, v89, v1
	v_fmac_f32_e32 v1, v113, v0
	v_add_f32_e32 v2, v2, v4
	v_add_f32_e32 v0, v3, v1
	s_waitcnt vmcnt(14)
	v_mov_b32_e32 v1, v232
	v_mov_b32_e32 v3, v233
	v_mul_f32_e32 v4, v89, v0
	v_fma_f32 v4, v113, v2, -v4
	v_mul_f32_e32 v2, v89, v2
	v_fmac_f32_e32 v2, v113, v0
	v_add_f32_e32 v1, v1, v4
	v_add_f32_e32 v0, v3, v2
	s_waitcnt vmcnt(12)
	v_mov_b32_e32 v2, v234
	v_mov_b32_e32 v3, v235
	v_mul_f32_e32 v4, v89, v0
	v_fma_f32 v4, v113, v1, -v4
	v_mul_f32_e32 v1, v89, v1
	v_fmac_f32_e32 v1, v113, v0
	v_add_f32_e32 v2, v2, v4
	v_add_f32_e32 v0, v3, v1
	s_waitcnt vmcnt(10)
	v_mov_b32_e32 v1, v236
	v_mov_b32_e32 v3, v237
	v_mul_f32_e32 v4, v89, v0
	v_fma_f32 v4, v113, v2, -v4
	v_mul_f32_e32 v2, v89, v2
	v_fmac_f32_e32 v2, v113, v0
	v_add_f32_e32 v1, v1, v4
	v_add_f32_e32 v0, v3, v2
	s_waitcnt vmcnt(8)
	v_mov_b32_e32 v2, v238
	v_mov_b32_e32 v3, v239
	v_mul_f32_e32 v4, v89, v0
	v_fma_f32 v4, v113, v1, -v4
	v_mul_f32_e32 v1, v89, v1
	v_fmac_f32_e32 v1, v113, v0
	v_add_f32_e32 v2, v2, v4
	v_lshl_add_u64 v[4:5], v[36:37], 0, s[0:1]
	v_add_f32_e32 v0, v3, v1
	s_waitcnt vmcnt(6)
	v_mov_b32_e32 v1, v240
	v_mov_b32_e32 v3, v241
	v_mul_f32_e32 v114, v89, v0
	v_fma_f32 v114, v113, v2, -v114
	v_mul_f32_e32 v2, v89, v2
	v_fmac_f32_e32 v2, v113, v0
	s_lshl_b64 s[0:1], s[92:93], 9
	v_add_f32_e32 v1, v1, v114
	v_add_f32_e32 v0, v3, v2
	v_lshl_add_u64 v[2:3], v[36:37], 0, s[0:1]
	s_waitcnt vmcnt(4)
	v_mov_b32_e32 v114, v242
	v_mov_b32_e32 v115, v243
	v_mul_f32_e32 v116, v89, v0
	v_fma_f32 v116, v113, v1, -v116
	v_mul_f32_e32 v1, v89, v1
	v_fmac_f32_e32 v1, v113, v0
	s_lshl_b64 s[0:1], s[24:25], 9
	v_add_f32_e32 v114, v114, v116
	v_add_f32_e32 v115, v115, v1
	v_lshl_add_u64 v[0:1], v[36:37], 0, s[0:1]
	s_waitcnt vmcnt(2)
	v_mov_b32_e32 v116, v244
	v_mov_b32_e32 v117, v245
	v_mul_f32_e32 v118, v89, v115
	s_lshl_b64 s[0:1], s[26:27], 9
	v_fma_f32 v118, v113, v114, -v118
	v_mul_f32_e32 v114, v89, v114
	v_lshl_add_u64 v[36:37], v[36:37], 0, s[0:1]
	v_fmac_f32_e32 v114, v113, v115
	s_waitcnt vmcnt(0)
	v_mov_b32_e32 v115, v160
	s_nop 0
	v_mov_b32_e32 v36, v161
	s_cmp_gt_u32 s59, 63
	v_add_f32_e32 v116, v116, v118
	v_add_f32_e32 v114, v117, v114
	v_mul_f32_e32 v37, v89, v114
	v_fma_f32 v37, v113, v116, -v37
	v_add_f32_e32 v37, v115, v37
	v_mul_f32_e32 v115, v89, v116
	v_fmac_f32_e32 v115, v113, v114
	v_add_f32_e32 v114, v36, v115
	v_lshl_or_b32 v36, s12, 9, v72
	v_add_u32_e32 v36, 0, v36
	ds_write2st64_b32 v36, v37, v114 offset1:1
	s_waitcnt lgkmcnt(0)
	s_barrier
; __device__ __forceinline__ void lam_pow(const Params& p, int g, int pp, float e, float& re, float& im) {
;   const float dt = __expf(p.in[17][g]), lr = p.in[15][g * 64 + pp], li = p.in[16][g * 64 + pp];
;   const float mag = expf(lr * dt * e); float sn, cs; sincosf(li * dt * e, &sn, &cs); re = mag * cs; im = mag * sn; }
; __device__ void ssm_scan_item(const Params& p, int b, int g, LAS unsigned char* lds) {
;     ...
;   if (w == 0) { float l5r, l5i; lam_pow(p, g, lane, 512.f, l5r, l5i); float sr = 0.f, si = 0.f; carry[lane] = 0.f; carry[64 + lane] = 0.f;
	s_cbranch_scc1 .LBB0_741
	global_load_dword v37, v53, s[38:39]
	v_readlane_b32 s4, v247, 17
	v_readlane_b32 s5, v247, 18
	v_readlane_b32 s6, v247, 19
	v_readlane_b32 s7, v247, 20
	v_readlane_b32 s8, v247, 21
	v_readlane_b32 s9, v247, 22
	v_readlane_b32 s10, v247, 23
	v_readlane_b32 s11, v247, 24
	v_readlane_b32 s12, v247, 25
	v_readlane_b32 s13, v247, 26
	v_readlane_b32 s14, v247, 27
	v_readlane_b32 s15, v247, 28
	v_readlane_b32 s16, v247, 29
	v_readlane_b32 s17, v247, 30
	v_readlane_b32 s18, v247, 31
	v_readlane_b32 s19, v247, 32
	v_lshl_add_u64 v[114:115], s[4:5], 0, v[52:53]
	global_load_dword v117, v[114:115], off
	v_readlane_b32 s4, v247, 1
	v_readlane_b32 s18, v247, 15
	v_readlane_b32 s19, v247, 16
	v_readlane_b32 s5, v247, 2
	v_readlane_b32 s6, v247, 3
	v_lshl_add_u64 v[114:115], s[18:19], 0, v[52:53]
	global_load_dword v115, v[114:115], off
	s_mov_b32 s19, 0xfe5163ab
	v_readlane_b32 s7, v247, 4
	v_readlane_b32 s8, v247, 5
	v_readlane_b32 s9, v247, 6
	v_readlane_b32 s10, v247, 7
	v_readlane_b32 s11, v247, 8
	v_readlane_b32 s12, v247, 9
	v_readlane_b32 s13, v247, 10
	v_readlane_b32 s14, v247, 11
	v_readlane_b32 s15, v247, 12
	v_readlane_b32 s16, v247, 13
	v_readlane_b32 s17, v247, 14
	s_waitcnt vmcnt(2)
	v_mul_f32_e32 v37, 0x3fb8aa3b, v37
	v_exp_f32_e32 v116, v37
	s_waitcnt vmcnt(1)
	v_mul_f32_e32 v37, v116, v117
	v_mul_f32_e32 v37, 0x44000000, v37
	v_and_b32_e32 v114, 0x7fffffff, v37
	v_cmp_nlt_f32_e64 s[0:1], |v37|, s33
	s_and_saveexec_b64 s[12:13], s[0:1]
	s_xor_b64 s[38:39], exec, s[12:13]
	s_cbranch_execz .LBB0_775
	v_lshrrev_b32_e32 v52, 23, v114
	v_add_u32_e32 v52, 0xffffff88, v52
	v_cmp_lt_u32_e32 vcc, 63, v52
	s_mov_b32 s4, 0x3c439041
	s_nop 0
	v_cndmask_b32_e32 v117, 0, v108, vcc
	v_add_u32_e32 v52, v117, v52
	v_cmp_lt_u32_e64 s[0:1], 31, v52
	s_nop 1
	v_cndmask_b32_e64 v117, 0, v109, s[0:1]
	v_add_u32_e32 v52, v117, v52
	v_cmp_lt_u32_e64 s[12:13], 31, v52
	s_nop 1
	v_cndmask_b32_e64 v117, 0, v109, s[12:13]
	v_add_u32_e32 v117, v117, v52
	v_and_b32_e32 v52, 0x7fffff, v114
	v_or_b32_e32 v130, 0x800000, v52
	v_mad_u64_u32 v[118:119], s[14:15], v130, s19, 0
	v_mov_b32_e32 v52, v119
	v_mad_u64_u32 v[120:121], s[14:15], v130, s4, v[52:53]
	v_mov_b32_e32 v52, v121
	s_mov_b32 s4, 0xdb629599
	v_mad_u64_u32 v[122:123], s[14:15], v130, s4, v[52:53]
	v_mov_b32_e32 v52, v123
	s_mov_b32 s4, 0xf534ddc0
	v_mad_u64_u32 v[124:125], s[14:15], v130, s4, v[52:53]
	v_mov_b32_e32 v52, v125
	s_mov_b32 s4, 0xfc2757d1
	v_mad_u64_u32 v[126:127], s[14:15], v130, s4, v[52:53]
	v_mov_b32_e32 v52, v127
	s_mov_b32 s4, 0x4e441529
	v_mad_u64_u32 v[128:129], s[14:15], v130, s4, v[52:53]
	v_mov_b32_e32 v52, v129
	s_mov_b32 s4, 0xa2f9836e
	v_mad_u64_u32 v[130:131], s[14:15], v130, s4, v[52:53]
	v_cndmask_b32_e32 v119, v128, v124, vcc
	v_cndmask_b32_e32 v52, v130, v126, vcc
	v_cndmask_b32_e32 v123, v131, v128, vcc
	v_cndmask_b32_e64 v121, v52, v119, s[0:1]
	v_cndmask_b32_e64 v52, v123, v52, s[0:1]
	v_cndmask_b32_e32 v123, v126, v122, vcc
	v_cndmask_b32_e64 v119, v119, v123, s[0:1]
	v_cndmask_b32_e64 v52, v52, v121, s[12:13]
	v_cndmask_b32_e64 v121, v121, v119, s[12:13]
	v_sub_u32_e32 v125, 32, v117
	v_alignbit_b32 v126, v52, v121, v125
	v_cmp_eq_u32_e64 s[14:15], 0, v117
	v_cndmask_b32_e32 v118, v122, v118, vcc
	s_nop 0
	v_cndmask_b32_e64 v117, v126, v52, s[14:15]
	v_cndmask_b32_e32 v52, v124, v120, vcc
	v_cndmask_b32_e64 v120, v123, v52, s[0:1]
	v_cndmask_b32_e64 v119, v119, v120, s[12:13]
	v_alignbit_b32 v123, v121, v119, v125
	v_cndmask_b32_e64 v121, v123, v121, s[14:15]
	v_bfe_u32 v126, v117, 29, 1
	v_cndmask_b32_e64 v52, v52, v118, s[0:1]
	v_alignbit_b32 v123, v117, v121, 30
	v_sub_u32_e32 v127, 0, v126
	v_cndmask_b32_e64 v52, v120, v52, s[12:13]
	v_xor_b32_e32 v123, v123, v127
	v_alignbit_b32 v118, v119, v52, v125
	v_cndmask_b32_e64 v118, v118, v119, s[14:15]
	v_ffbh_u32_e32 v120, v123
	v_alignbit_b32 v119, v121, v118, 30
	v_min_u32_e32 v120, 32, v120
	v_alignbit_b32 v52, v118, v52, 30
	v_xor_b32_e32 v119, v119, v127
	v_sub_u32_e32 v121, 31, v120
	v_xor_b32_e32 v52, v52, v127
	v_alignbit_b32 v122, v123, v119, v121
	v_alignbit_b32 v52, v119, v52, v121
	v_alignbit_b32 v118, v122, v52, 9
	v_ffbh_u32_e32 v119, v118
	v_min_u32_e32 v119, 32, v119
	v_lshrrev_b32_e32 v124, 29, v117
	v_not_b32_e32 v121, v119
	v_alignbit_b32 v52, v118, v52, v121
	v_lshlrev_b32_e32 v118, 31, v124
	v_or_b32_e32 v121, 0x33000000, v118
	v_add_lshl_u32 v119, v119, v120, 23
	v_lshrrev_b32_e32 v52, 9, v52
	v_sub_u32_e32 v119, v121, v119
	v_or_b32_e32 v118, 0.5, v118
	v_lshlrev_b32_e32 v120, 23, v120
	v_or_b32_e32 v52, v119, v52
	v_lshrrev_b32_e32 v119, 9, v122
	v_sub_u32_e32 v118, v118, v120
	v_or_b32_e32 v118, v119, v118
	v_mul_f32_e32 v119, 0x3fc90fda, v118
	v_fma_f32 v120, v118, s2, -v119
	v_fmac_f32_e32 v120, 0x33a22168, v118
	v_fmac_f32_e32 v120, 0x3fc90fda, v52
	v_lshrrev_b32_e32 v117, 30, v117
	v_add_f32_e32 v52, v119, v120
	v_add_u32_e32 v117, v126, v117

; #define LAS __attribute__((address_space(3)))
; __device__ __forceinline__ void attn_wg_item(const Params& p, int item, LAS unsigned char* lds) {
;     ...
;   LAS float* bl = (LAS float*)(lds + 2 * ATT_BUF + hh * 1536);
;   if (qt == 0) { const float* rb = p.in[14] + h * 513; for (int i = lane; i < 321; i += 64) bl[i] = rb[192 + i] * 1.4426950408889634f; }
.LBB0_812:
	s_lshr_b32 s36, s0, 8
	s_lshl_b32 s0, s40, 1
	s_and_b32 s37, s0, 6
	s_add_i32 s17, s37, s36
	s_cmp_lg_u32 s33, 0
	s_mul_i32 s35, s36, 0x600
	s_cbranch_scc1 .LBB0_816
	s_mul_i32 s0, s17, 0x201
	v_add_u32_e32 v2, s35, v143
	v_lshl_add_u64 v[0:1], s[0:1], 2, v[100:101]
	global_load_dword v4, v[0:1], off
	global_load_dword v5, v[0:1], off offset:256
	global_load_dword v6, v[0:1], off offset:512
	global_load_dword v7, v[0:1], off offset:768
	global_load_dword v8, v[0:1], off offset:1024
	v_cmp_eq_u32_e32 vcc, 0, v144
	s_and_saveexec_b64 s[18:19], vcc
	global_load_dword v9, v[0:1], off offset:1280
	s_waitcnt vmcnt(0)
	v_mul_f32_e32 v9, 0x3fb8aa3b, v9
	ds_write_b32 v2, v9 offset:1280
	s_mov_b64 exec, s[18:19]
	s_waitcnt vmcnt(0)
	v_mul_f32_e32 v4, 0x3fb8aa3b, v4
	v_mul_f32_e32 v5, 0x3fb8aa3b, v5
	v_mul_f32_e32 v6, 0x3fb8aa3b, v6
	v_mul_f32_e32 v7, 0x3fb8aa3b, v7
	v_mul_f32_e32 v8, 0x3fb8aa3b, v8
	ds_write_b32 v2, v4
	ds_write_b32 v2, v5 offset:256
	ds_write_b32 v2, v6 offset:512
	ds_write_b32 v2, v7 offset:768
	ds_write_b32 v2, v8 offset:1024
